# residual GEMM epilogues: the four base loads of each 16-row group issued together (8 round trips per tile instead of 32)
# speedup vs baseline: 1.0060x; 1.0060x over previous
.LBB0_224:
	s_ashr_i32 s14, s55, 3
	s_mul_hi_i32 s15, s14, 0x9000
	s_mul_i32 s14, s14, 0x9000
	v_lshl_or_b32 v134, s58, 8, v144
	s_add_u32 s14, s48, s14
	s_addc_u32 s15, s49, s15
	v_ashrrev_i32_e32 v135, 31, v134
	v_lshl_add_u32 v140, s55, 8, v142
	v_lshl_add_u64 v[136:137], v[134:135], 2, s[14:15]
	v_ashrrev_i32_e32 v141, 31, v140
	global_load_dwordx4 v[146:149], v[136:137], off
	v_lshlrev_b64 v[138:139], 10, v[140:141]
	v_lshl_add_u64 v[138:139], v[138:139], 0, v[134:135]
	v_lshlrev_b64 v[138:139], 2, v[138:139]
	v_lshl_add_u64 v[154:155], s[6:7], 0, v[138:139]
	global_load_dwordx4 v[150:153], v[154:155], off
	global_load_dwordx4 v[188:191], v[154:155], off offset:64
	global_load_dwordx4 v[192:195], v[154:155], off offset:512
	global_load_dwordx4 v[196:199], v[154:155], off offset:576
	global_load_dwordx4 v[172:175], v[136:137], off offset:64
	global_load_dwordx4 v[180:183], v[136:137], off offset:512
	global_load_dwordx4 v[184:187], v[136:137], off offset:576
	v_lshl_add_u64 v[176:177], s[26:27], 0, v[138:139]
	s_and_b64 vcc, exec, s[0:1]
	s_mov_b64 s[0:1], -1
	s_mov_b32 s87, 0x9000
	s_movk_i32 s86, 0x4000
	s_movk_i32 s72, 0x2000
	s_mov_b32 s73, 0x14000
	s_waitcnt vmcnt(0)
	v_pk_mul_f32 v[136:137], v[148:149], 0.5 op_sel_hi:[1,0]
	v_pk_mul_f32 v[138:139], v[146:147], 0.5 op_sel_hi:[1,0]
	v_pk_fma_f32 v[126:127], v[126:127], v[136:137], v[152:153]
	v_pk_fma_f32 v[124:125], v[124:125], v[138:139], v[150:151]
	global_store_dwordx4 v[176:177], v[124:127], off
	s_nop 1
	s_nop 0
	v_pk_mul_f32 v[124:125], v[174:175], 0.5 op_sel_hi:[1,0]
	v_pk_mul_f32 v[126:127], v[172:173], 0.5 op_sel_hi:[1,0]
	v_pk_fma_f32 v[122:123], v[122:123], v[124:125], v[190:191]
	v_pk_fma_f32 v[120:121], v[120:121], v[126:127], v[188:189]
	global_store_dwordx4 v[176:177], v[120:123], off offset:64
	s_nop 1
	s_nop 0
	v_pk_mul_f32 v[120:121], v[182:183], 0.5 op_sel_hi:[1,0]
	v_pk_mul_f32 v[122:123], v[180:181], 0.5 op_sel_hi:[1,0]
	v_pk_fma_f32 v[118:119], v[118:119], v[120:121], v[194:195]
	v_pk_fma_f32 v[116:117], v[116:117], v[122:123], v[192:193]
	global_store_dwordx4 v[176:177], v[116:119], off offset:512
	s_nop 1
	s_nop 0
	v_or_b32_e32 v116, 16, v140
	v_ashrrev_i32_e32 v117, 31, v116
	v_lshlrev_b64 v[116:117], 10, v[116:117]
	v_lshl_add_u64 v[116:117], v[116:117], 0, v[134:135]
	v_lshlrev_b64 v[150:151], 2, v[116:117]
	v_pk_mul_f32 v[116:117], v[186:187], 0.5 op_sel_hi:[1,0]
	v_pk_mul_f32 v[118:119], v[184:185], 0.5 op_sel_hi:[1,0]
	v_lshl_add_u64 v[152:153], s[6:7], 0, v[150:151]
	v_pk_fma_f32 v[106:107], v[106:107], v[116:117], v[198:199]
	v_pk_fma_f32 v[104:105], v[104:105], v[118:119], v[196:197]
	global_store_dwordx4 v[176:177], v[104:107], off offset:576
	global_load_dwordx4 v[104:107], v[152:153], off
	global_load_dwordx4 v[188:191], v[152:153], off offset:64
	global_load_dwordx4 v[192:195], v[152:153], off offset:512
	global_load_dwordx4 v[196:199], v[152:153], off offset:576
	v_lshl_add_u64 v[146:147], s[26:27], 0, v[150:151]
	s_waitcnt vmcnt(0)
	v_pk_fma_f32 v[106:107], v[114:115], v[136:137], v[106:107]
	v_pk_fma_f32 v[104:105], v[112:113], v[138:139], v[104:105]
	global_store_dwordx4 v[146:147], v[104:107], off
	v_pk_fma_f32 v[190:191], v[110:111], v[124:125], v[190:191]
	v_pk_fma_f32 v[188:189], v[108:109], v[126:127], v[188:189]
	global_store_dwordx4 v[146:147], v[188:191], off offset:64
	v_pk_fma_f32 v[102:103], v[102:103], v[120:121], v[194:195]
	v_pk_fma_f32 v[100:101], v[100:101], v[122:123], v[192:193]
	global_store_dwordx4 v[146:147], v[100:103], off offset:512
	v_or_b32_e32 v104, 32, v140
	v_ashrrev_i32_e32 v105, 31, v104
	v_lshlrev_b64 v[104:105], 10, v[104:105]
	v_lshl_add_u64 v[104:105], v[104:105], 0, v[134:135]
	v_lshlrev_b64 v[104:105], 2, v[104:105]
	v_lshl_add_u64 v[106:107], s[6:7], 0, v[104:105]
	v_pk_fma_f32 v[90:91], v[90:91], v[116:117], v[198:199]
	v_pk_fma_f32 v[88:89], v[88:89], v[118:119], v[196:197]
	global_store_dwordx4 v[146:147], v[88:91], off offset:576
	global_load_dwordx4 v[88:91], v[106:107], off
	global_load_dwordx4 v[188:191], v[106:107], off offset:64
	global_load_dwordx4 v[192:195], v[106:107], off offset:512
	global_load_dwordx4 v[196:199], v[106:107], off offset:576
	v_lshl_add_u64 v[100:101], s[26:27], 0, v[104:105]
	s_waitcnt vmcnt(0)
	v_pk_fma_f32 v[90:91], v[98:99], v[136:137], v[90:91]
	v_pk_fma_f32 v[88:89], v[96:97], v[138:139], v[88:89]
	global_store_dwordx4 v[100:101], v[88:91], off
	v_pk_fma_f32 v[190:191], v[94:95], v[124:125], v[190:191]
	v_pk_fma_f32 v[188:189], v[92:93], v[126:127], v[188:189]
	global_store_dwordx4 v[100:101], v[188:191], off offset:64
	v_pk_fma_f32 v[86:87], v[86:87], v[120:121], v[194:195]
	v_pk_fma_f32 v[84:85], v[84:85], v[122:123], v[192:193]
	global_store_dwordx4 v[100:101], v[84:87], off offset:512
	v_or_b32_e32 v88, 48, v140
	v_ashrrev_i32_e32 v89, 31, v88
	v_lshlrev_b64 v[88:89], 10, v[88:89]
	v_lshl_add_u64 v[88:89], v[88:89], 0, v[134:135]
	v_lshlrev_b64 v[88:89], 2, v[88:89]
	v_lshl_add_u64 v[90:91], s[6:7], 0, v[88:89]
	v_pk_fma_f32 v[74:75], v[74:75], v[116:117], v[198:199]
	v_pk_fma_f32 v[72:73], v[72:73], v[118:119], v[196:197]
	global_store_dwordx4 v[100:101], v[72:75], off offset:576
	global_load_dwordx4 v[72:75], v[90:91], off
	global_load_dwordx4 v[188:191], v[90:91], off offset:64
	global_load_dwordx4 v[192:195], v[90:91], off offset:512
	global_load_dwordx4 v[196:199], v[90:91], off offset:576
	v_lshl_add_u64 v[84:85], s[26:27], 0, v[88:89]
	s_waitcnt vmcnt(0)
	v_pk_fma_f32 v[74:75], v[82:83], v[136:137], v[74:75]
	v_pk_fma_f32 v[72:73], v[80:81], v[138:139], v[72:73]
	global_store_dwordx4 v[84:85], v[72:75], off
	v_pk_fma_f32 v[190:191], v[78:79], v[124:125], v[190:191]
	v_pk_fma_f32 v[188:189], v[76:77], v[126:127], v[188:189]
	global_store_dwordx4 v[84:85], v[188:191], off offset:64
	v_pk_fma_f32 v[70:71], v[70:71], v[120:121], v[194:195]
	v_pk_fma_f32 v[68:69], v[68:69], v[122:123], v[192:193]
	global_store_dwordx4 v[84:85], v[68:71], off offset:512
	v_add_u32_e32 v72, 0x80, v140
	v_ashrrev_i32_e32 v73, 31, v72
	v_lshlrev_b64 v[72:73], 10, v[72:73]
	v_lshl_add_u64 v[72:73], v[72:73], 0, v[134:135]
	v_lshlrev_b64 v[72:73], 2, v[72:73]
	v_lshl_add_u64 v[74:75], s[6:7], 0, v[72:73]
	v_pk_fma_f32 v[66:67], v[66:67], v[116:117], v[198:199]
	v_pk_fma_f32 v[64:65], v[64:65], v[118:119], v[196:197]
	global_store_dwordx4 v[84:85], v[64:67], off offset:576
	global_load_dwordx4 v[64:67], v[74:75], off
	global_load_dwordx4 v[188:191], v[74:75], off offset:64
	global_load_dwordx4 v[192:195], v[74:75], off offset:512
	global_load_dwordx4 v[196:199], v[74:75], off offset:576
	v_lshl_add_u64 v[68:69], s[26:27], 0, v[72:73]
	s_waitcnt vmcnt(0)
	v_pk_fma_f32 v[62:63], v[62:63], v[136:137], v[66:67]
	v_pk_fma_f32 v[60:61], v[60:61], v[138:139], v[64:65]
	global_store_dwordx4 v[68:69], v[60:63], off
	v_pk_fma_f32 v[58:59], v[58:59], v[124:125], v[190:191]
	v_pk_fma_f32 v[56:57], v[56:57], v[126:127], v[188:189]
	global_store_dwordx4 v[68:69], v[56:59], off offset:64
	v_pk_fma_f32 v[54:55], v[54:55], v[120:121], v[194:195]
	v_pk_fma_f32 v[52:53], v[52:53], v[122:123], v[192:193]
	global_store_dwordx4 v[68:69], v[52:55], off offset:512
	v_add_u32_e32 v56, 0x90, v140
	v_ashrrev_i32_e32 v57, 31, v56
	v_lshlrev_b64 v[56:57], 10, v[56:57]
	v_lshl_add_u64 v[56:57], v[56:57], 0, v[134:135]
	v_lshlrev_b64 v[56:57], 2, v[56:57]
	v_lshl_add_u64 v[58:59], s[6:7], 0, v[56:57]
	v_pk_fma_f32 v[42:43], v[42:43], v[116:117], v[198:199]
	v_pk_fma_f32 v[40:41], v[40:41], v[118:119], v[196:197]
	global_store_dwordx4 v[68:69], v[40:43], off offset:576
	global_load_dwordx4 v[40:43], v[58:59], off
	global_load_dwordx4 v[188:191], v[58:59], off offset:64
	global_load_dwordx4 v[192:195], v[58:59], off offset:512
	global_load_dwordx4 v[196:199], v[58:59], off offset:576
	v_lshl_add_u64 v[52:53], s[26:27], 0, v[56:57]
	s_waitcnt vmcnt(0)
	v_pk_fma_f32 v[42:43], v[50:51], v[136:137], v[42:43]
	v_pk_fma_f32 v[40:41], v[48:49], v[138:139], v[40:41]
	global_store_dwordx4 v[52:53], v[40:43], off
	v_pk_fma_f32 v[190:191], v[46:47], v[124:125], v[190:191]
	v_pk_fma_f32 v[188:189], v[44:45], v[126:127], v[188:189]
	global_store_dwordx4 v[52:53], v[188:191], off offset:64
	v_pk_fma_f32 v[38:39], v[38:39], v[120:121], v[194:195]
	v_pk_fma_f32 v[36:37], v[36:37], v[122:123], v[192:193]
	global_store_dwordx4 v[52:53], v[36:39], off offset:512
	v_add_u32_e32 v40, 0xa0, v140
	v_ashrrev_i32_e32 v41, 31, v40
	v_lshlrev_b64 v[40:41], 10, v[40:41]
	v_lshl_add_u64 v[40:41], v[40:41], 0, v[134:135]
	v_lshlrev_b64 v[40:41], 2, v[40:41]
	v_lshl_add_u64 v[42:43], s[6:7], 0, v[40:41]
	v_pk_fma_f32 v[26:27], v[26:27], v[116:117], v[198:199]
	v_pk_fma_f32 v[24:25], v[24:25], v[118:119], v[196:197]
	global_store_dwordx4 v[52:53], v[24:27], off offset:576
	global_load_dwordx4 v[24:27], v[42:43], off
	global_load_dwordx4 v[188:191], v[42:43], off offset:64
	global_load_dwordx4 v[192:195], v[42:43], off offset:512
	global_load_dwordx4 v[196:199], v[42:43], off offset:576
	v_lshl_add_u64 v[36:37], s[26:27], 0, v[40:41]
	s_waitcnt vmcnt(0)
	v_pk_fma_f32 v[26:27], v[34:35], v[136:137], v[26:27]
	v_pk_fma_f32 v[24:25], v[32:33], v[138:139], v[24:25]
	global_store_dwordx4 v[36:37], v[24:27], off
	v_pk_fma_f32 v[190:191], v[30:31], v[124:125], v[190:191]
	v_pk_fma_f32 v[188:189], v[28:29], v[126:127], v[188:189]
	global_store_dwordx4 v[36:37], v[188:191], off offset:64
	v_pk_fma_f32 v[22:23], v[22:23], v[120:121], v[194:195]
	v_pk_fma_f32 v[20:21], v[20:21], v[122:123], v[192:193]
	global_store_dwordx4 v[36:37], v[20:23], off offset:512
	v_add_u32_e32 v24, 0xb0, v140
	v_ashrrev_i32_e32 v25, 31, v24
	v_lshlrev_b64 v[24:25], 10, v[24:25]
	v_lshl_add_u64 v[24:25], v[24:25], 0, v[134:135]
	v_lshlrev_b64 v[24:25], 2, v[24:25]
	v_lshl_add_u64 v[26:27], s[6:7], 0, v[24:25]
	v_pk_fma_f32 v[10:11], v[10:11], v[116:117], v[198:199]
	v_pk_fma_f32 v[8:9], v[8:9], v[118:119], v[196:197]
	global_store_dwordx4 v[36:37], v[8:11], off offset:576
	global_load_dwordx4 v[8:11], v[26:27], off
	global_load_dwordx4 v[188:191], v[26:27], off offset:64
	global_load_dwordx4 v[192:195], v[26:27], off offset:512
	global_load_dwordx4 v[196:199], v[26:27], off offset:576
	v_lshl_add_u64 v[20:21], s[26:27], 0, v[24:25]
	s_waitcnt vmcnt(0)
	v_pk_fma_f32 v[10:11], v[18:19], v[136:137], v[10:11]
	v_pk_fma_f32 v[8:9], v[16:17], v[138:139], v[8:9]
	global_store_dwordx4 v[20:21], v[8:11], off
	v_pk_fma_f32 v[190:191], v[14:15], v[124:125], v[190:191]
	v_pk_fma_f32 v[188:189], v[12:13], v[126:127], v[188:189]
	global_store_dwordx4 v[20:21], v[188:191], off offset:64
	v_pk_fma_f32 v[6:7], v[6:7], v[120:121], v[194:195]
	v_pk_fma_f32 v[4:5], v[4:5], v[122:123], v[192:193]
	global_store_dwordx4 v[20:21], v[4:7], off offset:512
	v_pk_fma_f32 v[2:3], v[2:3], v[116:117], v[198:199]
	v_pk_fma_f32 v[0:1], v[0:1], v[118:119], v[196:197]
	global_store_dwordx4 v[20:21], v[0:3], off offset:576
	s_cbranch_vccnz .LBB0_209
	s_andn2_b64 vcc, exec, s[8:9]
	s_cbranch_vccnz .LBB0_208
	s_barrier
	s_branch .LBB0_208

.LBB0_973:
	s_ashr_i32 s9, s55, 3
	v_lshl_add_u32 v152, s55, 8, v154
	v_lshl_or_b32 v48, s58, 8, v172
	s_mul_hi_i32 s11, s9, 0x9000
	s_mul_i32 s9, s9, 0x9000
	v_ashrrev_i32_e32 v153, 31, v152
	s_add_u32 s16, s50, s9
	v_ashrrev_i32_e32 v49, 31, v48
	v_lshlrev_b64 v[174:175], 12, v[152:153]
	s_addc_u32 s17, s51, s11
	v_lshlrev_b64 v[150:151], 2, v[48:49]
	v_lshl_add_u64 v[174:175], s[26:27], 0, v[174:175]
	v_lshl_add_u64 v[48:49], s[16:17], 0, v[150:151]
	v_lshl_add_u64 v[180:181], v[174:175], 0, v[150:151]
	global_load_dwordx4 v[104:107], v[48:49], off
	global_load_dwordx4 v[96:99], v[48:49], off offset:64
	global_load_dwordx4 v[84:87], v[48:49], off offset:512
	s_nop 0
	global_load_dwordx4 v[48:51], v[48:49], off offset:576
	s_mov_b64 s[16:17], -1
	global_load_dwordx4 v[174:177], v[180:181], off
	global_load_dwordx4 v[188:191], v[180:181], off offset:64
	global_load_dwordx4 v[192:195], v[180:181], off offset:512
	global_load_dwordx4 v[196:199], v[180:181], off offset:576
	s_andn2_b64 vcc, exec, s[0:1]
	s_waitcnt vmcnt(0)
	v_pk_fma_f32 v[142:143], v[142:143], v[106:107], v[176:177]
	v_pk_fma_f32 v[140:141], v[140:141], v[104:105], v[174:175]
	global_store_dwordx4 v[180:181], v[140:143], off
	v_pk_fma_f32 v[138:139], v[138:139], v[98:99], v[190:191]
	v_pk_fma_f32 v[136:137], v[136:137], v[96:97], v[188:189]
	global_store_dwordx4 v[180:181], v[136:139], off offset:64
	v_pk_fma_f32 v[134:135], v[134:135], v[86:87], v[194:195]
	v_pk_fma_f32 v[132:133], v[132:133], v[84:85], v[192:193]
	global_store_dwordx4 v[180:181], v[132:135], off offset:512
	v_pk_fma_f32 v[130:131], v[130:131], v[50:51], v[198:199]
	v_pk_fma_f32 v[128:129], v[128:129], v[48:49], v[196:197]
	global_store_dwordx4 v[180:181], v[128:131], off offset:576
	s_nop 1
	v_or_b32_e32 v128, 16, v152
	v_ashrrev_i32_e32 v129, 31, v128
	v_lshlrev_b64 v[128:129], 12, v[128:129]
	v_lshl_add_u64 v[128:129], s[26:27], 0, v[128:129]
	v_lshl_add_u64 v[132:133], v[128:129], 0, v[150:151]
	global_load_dwordx4 v[128:131], v[132:133], off
	global_load_dwordx4 v[188:191], v[132:133], off offset:64
	global_load_dwordx4 v[192:195], v[132:133], off offset:512
	global_load_dwordx4 v[196:199], v[132:133], off offset:576
	s_waitcnt vmcnt(0)
	v_pk_fma_f32 v[126:127], v[126:127], v[106:107], v[130:131]
	v_pk_fma_f32 v[124:125], v[124:125], v[104:105], v[128:129]
	global_store_dwordx4 v[132:133], v[124:127], off
	v_pk_fma_f32 v[122:123], v[122:123], v[98:99], v[190:191]
	v_pk_fma_f32 v[120:121], v[120:121], v[96:97], v[188:189]
	global_store_dwordx4 v[132:133], v[120:123], off offset:64
	v_pk_fma_f32 v[118:119], v[118:119], v[86:87], v[194:195]
	v_pk_fma_f32 v[116:117], v[116:117], v[84:85], v[192:193]
	global_store_dwordx4 v[132:133], v[116:119], off offset:512
	v_pk_fma_f32 v[114:115], v[114:115], v[50:51], v[198:199]
	v_pk_fma_f32 v[112:113], v[112:113], v[48:49], v[196:197]
	global_store_dwordx4 v[132:133], v[112:115], off offset:576
	s_nop 1
	v_or_b32_e32 v112, 32, v152
	v_ashrrev_i32_e32 v113, 31, v112
	v_lshlrev_b64 v[112:113], 12, v[112:113]
	v_lshl_add_u64 v[112:113], s[26:27], 0, v[112:113]
	v_lshl_add_u64 v[116:117], v[112:113], 0, v[150:151]
	global_load_dwordx4 v[112:115], v[116:117], off
	global_load_dwordx4 v[188:191], v[116:117], off offset:64
	global_load_dwordx4 v[192:195], v[116:117], off offset:512
	global_load_dwordx4 v[196:199], v[116:117], off offset:576
	s_waitcnt vmcnt(0)
	v_pk_fma_f32 v[110:111], v[110:111], v[106:107], v[114:115]
	v_pk_fma_f32 v[108:109], v[108:109], v[104:105], v[112:113]
	global_store_dwordx4 v[116:117], v[108:111], off
	v_pk_fma_f32 v[102:103], v[102:103], v[98:99], v[190:191]
	v_pk_fma_f32 v[100:101], v[100:101], v[96:97], v[188:189]
	global_store_dwordx4 v[116:117], v[100:103], off offset:64
	v_pk_fma_f32 v[94:95], v[94:95], v[86:87], v[194:195]
	v_pk_fma_f32 v[92:93], v[92:93], v[84:85], v[192:193]
	global_store_dwordx4 v[116:117], v[92:95], off offset:512
	v_pk_fma_f32 v[90:91], v[90:91], v[50:51], v[198:199]
	v_pk_fma_f32 v[88:89], v[88:89], v[48:49], v[196:197]
	global_store_dwordx4 v[116:117], v[88:91], off offset:576
	s_nop 1
	v_or_b32_e32 v88, 48, v152
	v_ashrrev_i32_e32 v89, 31, v88
	v_lshlrev_b64 v[88:89], 12, v[88:89]
	v_lshl_add_u64 v[88:89], s[26:27], 0, v[88:89]
	v_lshl_add_u64 v[92:93], v[88:89], 0, v[150:151]
	global_load_dwordx4 v[88:91], v[92:93], off
	global_load_dwordx4 v[188:191], v[92:93], off offset:64
	global_load_dwordx4 v[192:195], v[92:93], off offset:512
	global_load_dwordx4 v[196:199], v[92:93], off offset:576
	s_waitcnt vmcnt(0)
	v_pk_fma_f32 v[82:83], v[82:83], v[106:107], v[90:91]
	v_pk_fma_f32 v[80:81], v[80:81], v[104:105], v[88:89]
	global_store_dwordx4 v[92:93], v[80:83], off
	v_pk_fma_f32 v[78:79], v[78:79], v[98:99], v[190:191]
	v_pk_fma_f32 v[76:77], v[76:77], v[96:97], v[188:189]
	global_store_dwordx4 v[92:93], v[76:79], off offset:64
	v_pk_fma_f32 v[74:75], v[74:75], v[86:87], v[194:195]
	v_pk_fma_f32 v[72:73], v[72:73], v[84:85], v[192:193]
	global_store_dwordx4 v[92:93], v[72:75], off offset:512
	v_pk_fma_f32 v[70:71], v[70:71], v[50:51], v[198:199]
	v_pk_fma_f32 v[68:69], v[68:69], v[48:49], v[196:197]
	global_store_dwordx4 v[92:93], v[68:71], off offset:576
	s_nop 1
	v_add_u32_e32 v68, 0x80, v152
	v_ashrrev_i32_e32 v69, 31, v68
	v_lshlrev_b64 v[68:69], 12, v[68:69]
	v_lshl_add_u64 v[68:69], s[26:27], 0, v[68:69]
	v_lshl_add_u64 v[72:73], v[68:69], 0, v[150:151]
	global_load_dwordx4 v[68:71], v[72:73], off
	global_load_dwordx4 v[188:191], v[72:73], off offset:64
	global_load_dwordx4 v[192:195], v[72:73], off offset:512
	global_load_dwordx4 v[196:199], v[72:73], off offset:576
	s_waitcnt vmcnt(0)
	v_pk_fma_f32 v[66:67], v[66:67], v[106:107], v[70:71]
	v_pk_fma_f32 v[64:65], v[64:65], v[104:105], v[68:69]
	global_store_dwordx4 v[72:73], v[64:67], off
	v_pk_fma_f32 v[62:63], v[62:63], v[98:99], v[190:191]
	v_pk_fma_f32 v[60:61], v[60:61], v[96:97], v[188:189]
	global_store_dwordx4 v[72:73], v[60:63], off offset:64
	v_pk_fma_f32 v[58:59], v[58:59], v[86:87], v[194:195]
	v_pk_fma_f32 v[56:57], v[56:57], v[84:85], v[192:193]
	global_store_dwordx4 v[72:73], v[56:59], off offset:512
	v_pk_fma_f32 v[54:55], v[54:55], v[50:51], v[198:199]
	v_pk_fma_f32 v[52:53], v[52:53], v[48:49], v[196:197]
	global_store_dwordx4 v[72:73], v[52:55], off offset:576
	s_nop 1
	v_add_u32_e32 v52, 0x90, v152
	v_ashrrev_i32_e32 v53, 31, v52
	v_lshlrev_b64 v[52:53], 12, v[52:53]
	v_lshl_add_u64 v[52:53], s[26:27], 0, v[52:53]
	v_lshl_add_u64 v[56:57], v[52:53], 0, v[150:151]
	global_load_dwordx4 v[52:55], v[56:57], off
	global_load_dwordx4 v[188:191], v[56:57], off offset:64
	global_load_dwordx4 v[192:195], v[56:57], off offset:512
	global_load_dwordx4 v[196:199], v[56:57], off offset:576
	s_waitcnt vmcnt(0)
	v_pk_fma_f32 v[46:47], v[46:47], v[106:107], v[54:55]
	v_pk_fma_f32 v[44:45], v[44:45], v[104:105], v[52:53]
	global_store_dwordx4 v[56:57], v[44:47], off
	v_pk_fma_f32 v[42:43], v[42:43], v[98:99], v[190:191]
	v_pk_fma_f32 v[40:41], v[40:41], v[96:97], v[188:189]
	global_store_dwordx4 v[56:57], v[40:43], off offset:64
	v_pk_fma_f32 v[38:39], v[38:39], v[86:87], v[194:195]
	v_pk_fma_f32 v[36:37], v[36:37], v[84:85], v[192:193]
	global_store_dwordx4 v[56:57], v[36:39], off offset:512
	v_pk_fma_f32 v[34:35], v[34:35], v[50:51], v[198:199]
	v_pk_fma_f32 v[32:33], v[32:33], v[48:49], v[196:197]
	global_store_dwordx4 v[56:57], v[32:35], off offset:576
	s_nop 1
	v_add_u32_e32 v32, 0xa0, v152
	v_ashrrev_i32_e32 v33, 31, v32
	v_lshlrev_b64 v[32:33], 12, v[32:33]
	v_lshl_add_u64 v[32:33], s[26:27], 0, v[32:33]
	v_lshl_add_u64 v[36:37], v[32:33], 0, v[150:151]
	global_load_dwordx4 v[32:35], v[36:37], off
	global_load_dwordx4 v[188:191], v[36:37], off offset:64
	global_load_dwordx4 v[192:195], v[36:37], off offset:512
	global_load_dwordx4 v[196:199], v[36:37], off offset:576
	s_waitcnt vmcnt(0)
	v_pk_fma_f32 v[30:31], v[30:31], v[106:107], v[34:35]
	v_pk_fma_f32 v[28:29], v[28:29], v[104:105], v[32:33]
	global_store_dwordx4 v[36:37], v[28:31], off
	v_pk_fma_f32 v[26:27], v[26:27], v[98:99], v[190:191]
	v_pk_fma_f32 v[24:25], v[24:25], v[96:97], v[188:189]
	global_store_dwordx4 v[36:37], v[24:27], off offset:64
	v_pk_fma_f32 v[22:23], v[22:23], v[86:87], v[194:195]
	v_pk_fma_f32 v[20:21], v[20:21], v[84:85], v[192:193]
	global_store_dwordx4 v[36:37], v[20:23], off offset:512
	v_pk_fma_f32 v[18:19], v[18:19], v[50:51], v[198:199]
	v_pk_fma_f32 v[16:17], v[16:17], v[48:49], v[196:197]
	global_store_dwordx4 v[36:37], v[16:19], off offset:576
	s_nop 1
	v_add_u32_e32 v16, 0xb0, v152
	v_ashrrev_i32_e32 v17, 31, v16
	v_lshlrev_b64 v[16:17], 12, v[16:17]
	v_lshl_add_u64 v[16:17], s[26:27], 0, v[16:17]
	v_lshl_add_u64 v[16:17], v[16:17], 0, v[150:151]
	global_load_dwordx4 v[18:21], v[16:17], off
	global_load_dwordx4 v[188:191], v[16:17], off offset:64
	global_load_dwordx4 v[192:195], v[16:17], off offset:512
	global_load_dwordx4 v[196:199], v[16:17], off offset:576
	s_waitcnt vmcnt(0)
	v_pk_fma_f32 v[14:15], v[14:15], v[106:107], v[20:21]
	v_pk_fma_f32 v[12:13], v[12:13], v[104:105], v[18:19]
	global_store_dwordx4 v[16:17], v[12:15], off
	v_pk_fma_f32 v[10:11], v[10:11], v[98:99], v[190:191]
	v_pk_fma_f32 v[8:9], v[8:9], v[96:97], v[188:189]
	global_store_dwordx4 v[16:17], v[8:11], off offset:64
	v_pk_fma_f32 v[6:7], v[6:7], v[86:87], v[194:195]
	v_pk_fma_f32 v[4:5], v[4:5], v[84:85], v[192:193]
	global_store_dwordx4 v[16:17], v[4:7], off offset:512
	v_pk_fma_f32 v[2:3], v[2:3], v[50:51], v[198:199]
	v_pk_fma_f32 v[0:1], v[0:1], v[48:49], v[196:197]
	global_store_dwordx4 v[16:17], v[0:3], off offset:576
	s_cbranch_vccnz .LBB0_962
	s_andn2_b64 vcc, exec, s[4:5]
	s_cbranch_vccnz .LBB0_961
	s_barrier
	s_branch .LBB0_961

.LBB0_1175:
	s_ashr_i32 s12, s53, 3
	v_lshl_or_b32 v134, s54, 8, v172
	s_mul_hi_i32 s13, s12, 0x9000
	s_mul_i32 s12, s12, 0x9000
	s_add_u32 s12, s46, s12
	v_ashrrev_i32_e32 v135, 31, v134
	s_addc_u32 s13, s47, s13
	v_lshlrev_b64 v[146:147], 2, v[134:135]
	v_lshl_add_u64 v[152:153], s[12:13], 0, v[146:147]
	global_load_dwordx4 v[134:137], v[152:153], off
	global_load_dwordx4 v[174:177], v[152:153], off offset:576
	s_mov_b64 s[12:13], -1
	s_and_b64 vcc, exec, s[0:1]
	s_movk_i32 s72, 0x2000
	s_mov_b32 s73, 0x14000
	s_waitcnt vmcnt(0)
	v_pk_mul_f32 v[148:149], v[136:137], 0.5 op_sel_hi:[1,0]
	v_pk_mul_f32 v[150:151], v[134:135], 0.5 op_sel_hi:[1,0]
	global_load_dwordx4 v[134:137], v[152:153], off offset:64
	s_waitcnt vmcnt(0)
	v_pk_mul_f32 v[142:143], v[136:137], 0.5 op_sel_hi:[1,0]
	v_pk_mul_f32 v[144:145], v[134:135], 0.5 op_sel_hi:[1,0]
	global_load_dwordx4 v[134:137], v[152:153], off offset:512
	v_lshl_add_u32 v152, s53, 8, v154
	v_ashrrev_i32_e32 v153, 31, v152
	s_waitcnt vmcnt(0)
	v_pk_mul_f32 v[138:139], v[136:137], 0.5 op_sel_hi:[1,0]
	v_pk_mul_f32 v[136:137], v[174:175], 0.5 op_sel_hi:[1,0]
	v_lshlrev_b64 v[174:175], 12, v[152:153]
	v_lshl_add_u64 v[174:175], s[26:27], 0, v[174:175]
	v_lshl_add_u64 v[180:181], v[174:175], 0, v[146:147]
	v_pk_mul_f32 v[140:141], v[134:135], 0.5 op_sel_hi:[1,0]
	v_pk_mul_f32 v[134:135], v[176:177], 0.5 op_sel_hi:[1,0]
	global_load_dwordx4 v[174:177], v[180:181], off
	global_load_dwordx4 v[188:191], v[180:181], off offset:64
	global_load_dwordx4 v[192:195], v[180:181], off offset:512
	global_load_dwordx4 v[196:199], v[180:181], off offset:576
	s_waitcnt vmcnt(0)
	v_pk_fma_f32 v[126:127], v[126:127], v[148:149], v[176:177]
	v_pk_fma_f32 v[124:125], v[124:125], v[150:151], v[174:175]
	global_store_dwordx4 v[180:181], v[124:127], off
	v_pk_fma_f32 v[122:123], v[122:123], v[142:143], v[190:191]
	v_pk_fma_f32 v[120:121], v[120:121], v[144:145], v[188:189]
	global_store_dwordx4 v[180:181], v[120:123], off offset:64
	v_pk_fma_f32 v[118:119], v[118:119], v[138:139], v[194:195]
	v_pk_fma_f32 v[116:117], v[116:117], v[140:141], v[192:193]
	global_store_dwordx4 v[180:181], v[116:119], off offset:512
	v_pk_fma_f32 v[114:115], v[114:115], v[134:135], v[198:199]
	v_pk_fma_f32 v[112:113], v[112:113], v[136:137], v[196:197]
	global_store_dwordx4 v[180:181], v[112:115], off offset:576
	s_nop 1
	v_or_b32_e32 v112, 16, v152
	v_ashrrev_i32_e32 v113, 31, v112
	v_lshlrev_b64 v[112:113], 12, v[112:113]
	v_lshl_add_u64 v[112:113], s[26:27], 0, v[112:113]
	v_lshl_add_u64 v[116:117], v[112:113], 0, v[146:147]
	global_load_dwordx4 v[112:115], v[116:117], off
	global_load_dwordx4 v[188:191], v[116:117], off offset:64
	global_load_dwordx4 v[192:195], v[116:117], off offset:512
	global_load_dwordx4 v[196:199], v[116:117], off offset:576
	s_waitcnt vmcnt(0)
	v_pk_fma_f32 v[110:111], v[110:111], v[148:149], v[114:115]
	v_pk_fma_f32 v[108:109], v[108:109], v[150:151], v[112:113]
	global_store_dwordx4 v[116:117], v[108:111], off
	v_pk_fma_f32 v[106:107], v[106:107], v[142:143], v[190:191]
	v_pk_fma_f32 v[104:105], v[104:105], v[144:145], v[188:189]
	global_store_dwordx4 v[116:117], v[104:107], off offset:64
	v_pk_fma_f32 v[102:103], v[102:103], v[138:139], v[194:195]
	v_pk_fma_f32 v[100:101], v[100:101], v[140:141], v[192:193]
	global_store_dwordx4 v[116:117], v[100:103], off offset:512
	v_pk_fma_f32 v[98:99], v[98:99], v[134:135], v[198:199]
	v_pk_fma_f32 v[96:97], v[96:97], v[136:137], v[196:197]
	global_store_dwordx4 v[116:117], v[96:99], off offset:576
	s_nop 1
	v_or_b32_e32 v96, 32, v152
	v_ashrrev_i32_e32 v97, 31, v96
	v_lshlrev_b64 v[96:97], 12, v[96:97]
	v_lshl_add_u64 v[96:97], s[26:27], 0, v[96:97]
	v_lshl_add_u64 v[100:101], v[96:97], 0, v[146:147]
	global_load_dwordx4 v[96:99], v[100:101], off
	global_load_dwordx4 v[188:191], v[100:101], off offset:64
	global_load_dwordx4 v[192:195], v[100:101], off offset:512
	global_load_dwordx4 v[196:199], v[100:101], off offset:576
	s_waitcnt vmcnt(0)
	v_pk_fma_f32 v[94:95], v[94:95], v[148:149], v[98:99]
	v_pk_fma_f32 v[92:93], v[92:93], v[150:151], v[96:97]
	global_store_dwordx4 v[100:101], v[92:95], off
	v_pk_fma_f32 v[90:91], v[90:91], v[142:143], v[190:191]
	v_pk_fma_f32 v[88:89], v[88:89], v[144:145], v[188:189]
	global_store_dwordx4 v[100:101], v[88:91], off offset:64
	v_pk_fma_f32 v[86:87], v[86:87], v[138:139], v[194:195]
	v_pk_fma_f32 v[84:85], v[84:85], v[140:141], v[192:193]
	global_store_dwordx4 v[100:101], v[84:87], off offset:512
	v_pk_fma_f32 v[82:83], v[82:83], v[134:135], v[198:199]
	v_pk_fma_f32 v[80:81], v[80:81], v[136:137], v[196:197]
	global_store_dwordx4 v[100:101], v[80:83], off offset:576
	s_nop 1
	v_or_b32_e32 v80, 48, v152
	v_ashrrev_i32_e32 v81, 31, v80
	v_lshlrev_b64 v[80:81], 12, v[80:81]
	v_lshl_add_u64 v[80:81], s[26:27], 0, v[80:81]
	v_lshl_add_u64 v[84:85], v[80:81], 0, v[146:147]
	global_load_dwordx4 v[80:83], v[84:85], off
	global_load_dwordx4 v[188:191], v[84:85], off offset:64
	global_load_dwordx4 v[192:195], v[84:85], off offset:512
	global_load_dwordx4 v[196:199], v[84:85], off offset:576
	s_waitcnt vmcnt(0)
	v_pk_fma_f32 v[78:79], v[78:79], v[148:149], v[82:83]
	v_pk_fma_f32 v[76:77], v[76:77], v[150:151], v[80:81]
	global_store_dwordx4 v[84:85], v[76:79], off
	v_pk_fma_f32 v[74:75], v[74:75], v[142:143], v[190:191]
	v_pk_fma_f32 v[72:73], v[72:73], v[144:145], v[188:189]
	global_store_dwordx4 v[84:85], v[72:75], off offset:64
	v_pk_fma_f32 v[70:71], v[70:71], v[138:139], v[194:195]
	v_pk_fma_f32 v[68:69], v[68:69], v[140:141], v[192:193]
	global_store_dwordx4 v[84:85], v[68:71], off offset:512
	v_pk_fma_f32 v[66:67], v[66:67], v[134:135], v[198:199]
	v_pk_fma_f32 v[64:65], v[64:65], v[136:137], v[196:197]
	global_store_dwordx4 v[84:85], v[64:67], off offset:576
	s_nop 1
	v_add_u32_e32 v64, 0x80, v152
	v_ashrrev_i32_e32 v65, 31, v64
	v_lshlrev_b64 v[64:65], 12, v[64:65]
	v_lshl_add_u64 v[64:65], s[26:27], 0, v[64:65]
	v_lshl_add_u64 v[68:69], v[64:65], 0, v[146:147]
	global_load_dwordx4 v[64:67], v[68:69], off
	global_load_dwordx4 v[188:191], v[68:69], off offset:64
	global_load_dwordx4 v[192:195], v[68:69], off offset:512
	global_load_dwordx4 v[196:199], v[68:69], off offset:576
	s_waitcnt vmcnt(0)
	v_pk_fma_f32 v[62:63], v[62:63], v[148:149], v[66:67]
	v_pk_fma_f32 v[60:61], v[60:61], v[150:151], v[64:65]
	global_store_dwordx4 v[68:69], v[60:63], off
	v_pk_fma_f32 v[58:59], v[58:59], v[142:143], v[190:191]
	v_pk_fma_f32 v[56:57], v[56:57], v[144:145], v[188:189]
	global_store_dwordx4 v[68:69], v[56:59], off offset:64
	v_pk_fma_f32 v[54:55], v[54:55], v[138:139], v[194:195]
	v_pk_fma_f32 v[52:53], v[52:53], v[140:141], v[192:193]
	global_store_dwordx4 v[68:69], v[52:55], off offset:512
	v_pk_fma_f32 v[50:51], v[50:51], v[134:135], v[198:199]
	v_pk_fma_f32 v[48:49], v[48:49], v[136:137], v[196:197]
	global_store_dwordx4 v[68:69], v[48:51], off offset:576
	s_nop 1
	v_add_u32_e32 v48, 0x90, v152
	v_ashrrev_i32_e32 v49, 31, v48
	v_lshlrev_b64 v[48:49], 12, v[48:49]
	v_lshl_add_u64 v[48:49], s[26:27], 0, v[48:49]
	v_lshl_add_u64 v[52:53], v[48:49], 0, v[146:147]
	global_load_dwordx4 v[48:51], v[52:53], off
	global_load_dwordx4 v[188:191], v[52:53], off offset:64
	global_load_dwordx4 v[192:195], v[52:53], off offset:512
	global_load_dwordx4 v[196:199], v[52:53], off offset:576
	s_waitcnt vmcnt(0)
	v_pk_fma_f32 v[46:47], v[46:47], v[148:149], v[50:51]
	v_pk_fma_f32 v[44:45], v[44:45], v[150:151], v[48:49]
	global_store_dwordx4 v[52:53], v[44:47], off
	v_pk_fma_f32 v[42:43], v[42:43], v[142:143], v[190:191]
	v_pk_fma_f32 v[40:41], v[40:41], v[144:145], v[188:189]
	global_store_dwordx4 v[52:53], v[40:43], off offset:64
	v_pk_fma_f32 v[38:39], v[38:39], v[138:139], v[194:195]
	v_pk_fma_f32 v[36:37], v[36:37], v[140:141], v[192:193]
	global_store_dwordx4 v[52:53], v[36:39], off offset:512
	v_pk_fma_f32 v[34:35], v[34:35], v[134:135], v[198:199]
	v_pk_fma_f32 v[32:33], v[32:33], v[136:137], v[196:197]
	global_store_dwordx4 v[52:53], v[32:35], off offset:576
	s_nop 1
	v_add_u32_e32 v32, 0xa0, v152
	v_ashrrev_i32_e32 v33, 31, v32
	v_lshlrev_b64 v[32:33], 12, v[32:33]
	v_lshl_add_u64 v[32:33], s[26:27], 0, v[32:33]
	v_lshl_add_u64 v[36:37], v[32:33], 0, v[146:147]
	global_load_dwordx4 v[32:35], v[36:37], off
	global_load_dwordx4 v[188:191], v[36:37], off offset:64
	global_load_dwordx4 v[192:195], v[36:37], off offset:512
	global_load_dwordx4 v[196:199], v[36:37], off offset:576
	s_waitcnt vmcnt(0)
	v_pk_fma_f32 v[30:31], v[30:31], v[148:149], v[34:35]
	v_pk_fma_f32 v[28:29], v[28:29], v[150:151], v[32:33]
	global_store_dwordx4 v[36:37], v[28:31], off
	v_pk_fma_f32 v[26:27], v[26:27], v[142:143], v[190:191]
	v_pk_fma_f32 v[24:25], v[24:25], v[144:145], v[188:189]
	global_store_dwordx4 v[36:37], v[24:27], off offset:64
	v_pk_fma_f32 v[22:23], v[22:23], v[138:139], v[194:195]
	v_pk_fma_f32 v[20:21], v[20:21], v[140:141], v[192:193]
	global_store_dwordx4 v[36:37], v[20:23], off offset:512
	v_pk_fma_f32 v[18:19], v[18:19], v[134:135], v[198:199]
	v_pk_fma_f32 v[16:17], v[16:17], v[136:137], v[196:197]
	global_store_dwordx4 v[36:37], v[16:19], off offset:576
	s_nop 1
	v_add_u32_e32 v16, 0xb0, v152
	v_ashrrev_i32_e32 v17, 31, v16
	v_lshlrev_b64 v[16:17], 12, v[16:17]
	v_lshl_add_u64 v[16:17], s[26:27], 0, v[16:17]
	v_lshl_add_u64 v[16:17], v[16:17], 0, v[146:147]
	global_load_dwordx4 v[18:21], v[16:17], off
	global_load_dwordx4 v[188:191], v[16:17], off offset:64
	global_load_dwordx4 v[192:195], v[16:17], off offset:512
	global_load_dwordx4 v[196:199], v[16:17], off offset:576
	s_waitcnt vmcnt(0)
	v_pk_fma_f32 v[14:15], v[14:15], v[148:149], v[20:21]
	v_pk_fma_f32 v[12:13], v[12:13], v[150:151], v[18:19]
	global_store_dwordx4 v[16:17], v[12:15], off
	v_pk_fma_f32 v[10:11], v[10:11], v[142:143], v[190:191]
	v_pk_fma_f32 v[8:9], v[8:9], v[144:145], v[188:189]
	global_store_dwordx4 v[16:17], v[8:11], off offset:64
	v_pk_fma_f32 v[6:7], v[6:7], v[138:139], v[194:195]
	v_pk_fma_f32 v[4:5], v[4:5], v[140:141], v[192:193]
	global_store_dwordx4 v[16:17], v[4:7], off offset:512
	v_pk_fma_f32 v[2:3], v[2:3], v[134:135], v[198:199]
	v_pk_fma_f32 v[0:1], v[0:1], v[136:137], v[196:197]
	global_store_dwordx4 v[16:17], v[0:3], off offset:576
	s_cbranch_vccnz .LBB0_1160
	s_andn2_b64 vcc, exec, s[6:7]
	s_cbranch_vccnz .LBB0_1159
	s_barrier
	s_branch .LBB0_1159
